# lever 7 (address arithmetic off the VALU): attention K/V ring LDS-DMA sources use saddr + 32-bit lane offset; wave-uniform tile advance and per-DMA constants kept in SGPRs by SALU (6 v_lshl_add_u64 pe
# speedup vs baseline: 1.0072x; 1.0072x over previous
; #define AT_ISSUE_K(tt) do { const unsigned so_ = (unsigned)(((tt) & 3) * AT_SLOT); const bf16_t* kp_ = kgp + (size_t)(tt) * 64 * DM; \
;         glds16(kp_, (unsigned)__builtin_amdgcn_readfirstlane(kdst + so_)); glds16(kp_ + kx1, (unsigned)__builtin_amdgcn_readfirstlane(kdst + so_ + 1024)); } while (0)
; #define AT_ISSUE_V(tt) do { const unsigned so_ = (unsigned)(((tt) & 3) * AT_SLOT); const bf16_t* vp_ = vgp + (tt) * 64; \
;         glds16(vp_, (unsigned)__builtin_amdgcn_readfirstlane(vdst + so_)); glds16(vp_ + vx1, (unsigned)__builtin_amdgcn_readfirstlane(vdst + so_ + 1024)); } while (0)
; #define AT_BAR(N) asm volatile("s_waitcnt vmcnt(" #N ") lgkmcnt(0)\n\ts_barrier" ::: "memory")
; template <bool STORE> __device__ __forceinline__ void attn_unit(LAS unsigned char* lds, bf16_t* Q, const bf16_t* Kg, const bf16_t* VT, const float* subg, float lam, float outscale, int unit, const int wave_s) {
;     ...
;     const unsigned lds0 = (unsigned)(uintptr_t)lds;
;     const bf16_t* kgp; const bf16_t* vgp;
;     { const int kr = 8 * wid + (lane >> 4), kc = (lane & 15) ^ (kr & 15); kgp = Kg + (size_t)(b * SEQ + kr) * DM + h * 128 + kc * 8;
;       const int vr = 16 * wid + (lane >> 3), vc = (lane & 7) ^ ((vr >> 1) & 7); vgp = VT + (size_t)(h * 128 + vr) * T + b * SEQ + vc * 8; }
;     const int kx1 = ((((lane & 15) ^ ((8 * wid + (lane >> 4) + 4) & 15)) - ((lane & 15) ^ ((8 * wid + (lane >> 4)) & 15))) * 8) + 4 * DM;
;     const int vx1 = ((((lane & 7) ^ (((16 * wid + (lane >> 3) + 8) >> 1) & 7)) - ((lane & 7) ^ (((16 * wid + (lane >> 3)) >> 1) & 7))) * 8) + 8 * T;
;     const unsigned kdst = lds0 + wid * 2048, vdst = lds0 + AT_VOFF + wid * 2048;
;     ...
;     AT_ISSUE_K(0); AT_ISSUE_V(0); AT_ISSUE_K(1); AT_ISSUE_V(1); AT_ISSUE_K(2); AT_ISSUE_V(2); AT_ISSUE_K(3);
;     AT_BAR(8);
;     f32x16 o[4]; o[0] = f32x16{}; o[1] = f32x16{}; o[2] = f32x16{}; o[3] = f32x16{};
;     float mref = sself + 6.0f, lsum = 0.f;
;     const int koff = q * 256 + (((map * 8 + hi) ^ (q & 15)) << 4), voff = AT_VOFF + q * 128 + ((hi ^ ((q >> 1) & 7)) << 4);
;     const float qposf = (float)(qrow0 + q - 4 * hi);
;     f32x16 x0, x1, n0, n1;
.LBB0_581:
	v_lshlrev_b32_e32 v0, 7, v3
	v_lshrrev_b32_e32 v3, 1, v219
	v_bitop3_b32 v2, v2, v3, 7 bitop3:0x78
	s_lshr_b32 s16, s12, 6
	v_lshl_or_b32 v215, v2, 4, v0
	s_waitcnt lgkmcnt(0)
	s_barrier
	s_cmpk_lt_u32 s12, 0xc0
	s_mov_b64 s[12:13], 0xf80
	v_or_b32_e32 v214, 0x10000, v215
	v_lshl_add_u64 v[174:175], v[182:183], 0, s[12:13]
	v_add_f32_e32 v167, v166, v166
	v_add_u32_e32 v204, 0, v214
	v_lshl_add_u64 v[176:177], v[172:173], 1, v[174:175]
	v_fma_f32 v185, 2.0, v166, v167
	v_xor_b32_e32 v203, 0x10020, v215
	v_xor_b32_e32 v202, 0x10040, v215
	v_xor_b32_e32 v179, 0x10060, v215
	s_cbranch_scc1 .LBB0_605
	v_xor_b32_e32 v0, 0x10020, v215
	v_readlane_b32 s12, v253, 23
	v_mov_b32_e32 v184, v166
	v_mov_b32_e32 v2, v167
	v_mov_b32_e32 v3, v185
	v_add_u32_e32 v220, 0, v0
	v_xor_b32_e32 v0, 0x10040, v215
	s_add_i32 s12, s34, s12
	v_add_f32_e32 v186, v184, v2
	v_add_f32_e32 v187, v185, v3
	v_add_u32_e32 v221, 0, v0
	v_xor_b32_e32 v0, 0x10060, v215
	v_add_u32_e32 v2, s12, v216
	v_add_u32_e32 v222, 0, v0
	v_ashrrev_i32_e32 v3, 31, v2
	v_add_u32_e32 v0, s19, v218
	v_lshlrev_b64 v[188:189], 11, v[2:3]
	v_lshlrev_b64 v[2:3], 15, v[0:1]
	v_lshl_or_b32 v2, v217, 4, v2
	v_mov_b32_e32 v14, v1
	v_mov_b32_e32 v15, v1
	v_add_f32_e32 v168, v187, v187
	s_and_b32 s12, s18, 0x700
	v_lshl_add_u64 v[190:191], s[34:35], 1, v[2:3]
	v_mov_b32_e32 v0, v1
	v_mov_b32_e32 v2, v1
	v_mov_b32_e32 v3, v1
	v_mov_b32_e32 v4, v1
	v_mov_b32_e32 v5, v1
	v_mov_b32_e32 v6, v1
	v_mov_b32_e32 v7, v1
	v_mov_b32_e32 v8, v1
	v_mov_b32_e32 v9, v1
	v_mov_b32_e32 v10, v1
	v_mov_b32_e32 v11, v1
	v_mov_b32_e32 v12, v1
	v_mov_b32_e32 v13, v1
	v_mov_b64_e32 v[78:79], v[14:15]
	v_mov_b64_e32 v[62:63], v[14:15]
	v_mov_b64_e32 v[46:47], v[14:15]
	v_mov_b64_e32 v[30:31], v[14:15]
	v_fmac_f32_e32 v168, 2.0, v187
	v_or3_b32 v188, v188, s12, v178
	s_mov_b32 s20, 0
	v_mov_b32_e32 v184, 0
	s_mov_b32 s21, 0x14000
	s_movk_i32 s28, 0x80
	v_mov_b64_e32 v[76:77], v[12:13]
	v_mov_b64_e32 v[74:75], v[10:11]
	v_mov_b64_e32 v[72:73], v[8:9]
	v_mov_b64_e32 v[70:71], v[6:7]
	v_mov_b64_e32 v[68:69], v[4:5]
	v_mov_b64_e32 v[66:67], v[2:3]
	v_mov_b64_e32 v[64:65], v[0:1]
	v_mov_b64_e32 v[60:61], v[12:13]
	v_mov_b64_e32 v[58:59], v[10:11]
	v_mov_b64_e32 v[56:57], v[8:9]
	v_mov_b64_e32 v[54:55], v[6:7]
	v_mov_b64_e32 v[52:53], v[4:5]
	v_mov_b64_e32 v[50:51], v[2:3]
	v_mov_b64_e32 v[48:49], v[0:1]
	v_mov_b64_e32 v[44:45], v[12:13]
	v_mov_b64_e32 v[42:43], v[10:11]
	v_mov_b64_e32 v[40:41], v[8:9]
	v_mov_b64_e32 v[38:39], v[6:7]
	v_mov_b64_e32 v[36:37], v[4:5]
	v_mov_b64_e32 v[34:35], v[2:3]
	v_mov_b64_e32 v[32:33], v[0:1]
	v_mov_b64_e32 v[28:29], v[12:13]
	v_mov_b64_e32 v[26:27], v[10:11]
	v_mov_b64_e32 v[24:25], v[8:9]
	v_mov_b64_e32 v[22:23], v[6:7]
	v_mov_b64_e32 v[20:21], v[4:5]
	v_mov_b64_e32 v[18:19], v[2:3]
	v_mov_b64_e32 v[16:17], v[0:1]
	s_mov_b32 s84, s10
	s_mov_b32 s85, s11
	s_mov_b32 s86, s10
	s_mov_b32 s87, s11

.LBB0_587:
	s_andn2_b64 vcc, exec, s[42:43]
	v_lshl_add_u32 v4, v170, 1, v188
	v_lshl_add_u32 v2, v172, 1, v190
	s_cbranch_vccnz .LBB0_589
	s_add_i32 s30, s21, 0xfffec000
	s_and_b32 s30, s30, 0x8000
	s_add_i32 s30, s30, s37
	s_add_u32 s94, s84, s56
	s_addc_u32 s95, s85, s57
	s_mov_b32 m0, s30
	s_nop 0
	global_load_lds_dwordx4 v188, s[94:95]
	s_addk_i32 s30, 0x400
	s_mov_b32 m0, s30
	s_nop 0
	global_load_lds_dwordx4 v4, s[94:95]
	s_add_i32 s30, s21, 0xffff8000
	s_and_b32 s30, s30, 0xc000
	s_add_u32 s94, s86, s74
	s_addc_u32 s95, s87, s75
	s_add_i32 s30, s30, s3
	s_mov_b32 m0, s30
	s_nop 0
	global_load_lds_dwordx4 v190, s[94:95]
	s_addk_i32 s30, 0x400
	s_mov_b32 m0, s30
	s_nop 0
	global_load_lds_dwordx4 v2, s[94:95]

.LBB0_594:
	s_and_b32 s42, s21, 0xc000
	s_add_u32 s94, s84, 0x8da0000
	s_addc_u32 s95, s85, 0
	s_add_i32 s42, s42, s37
	s_mov_b32 m0, s42
	s_nop 0
	global_load_lds_dwordx4 v188, s[94:95]
	s_addk_i32 s42, 0x400
	s_mov_b32 m0, s42
	s_nop 0
	global_load_lds_dwordx4 v4, s[94:95]
	s_add_u32 s94, s86, s88
	s_addc_u32 s95, s87, s89
	s_add_i32 s36, s36, s3
	s_mov_b32 m0, s36
	s_nop 0
	global_load_lds_dwordx4 v190, s[94:95]
	s_addk_i32 s36, 0x400
	s_mov_b32 m0, s36
	s_nop 0
	global_load_lds_dwordx4 v2, s[94:95]

; template <bool STORE> __device__ __forceinline__ void attn_unit(LAS unsigned char* lds, bf16_t* Q, const bf16_t* Kg, const bf16_t* VT, const float* subg, float lam, float outscale, int unit, const int wave_s) {
;     ...
;         for (; t + 2 < td; t += 2) { AT_BODY(0, t, 1.0f, x0, x1, n0, n1); AT_BODY(0, t + 1, 1.0f, n0, n1, x0, x1); }
;         if (t + 1 < td) { AT_BODY(0, t, 1.0f, x0, x1, n0, n1); x0 = n0; x1 = n1; ++t; }
;         if (td >= 1) { AT_BODY(1, t, 0.0f, x0, x1, n0, n1); x0 = n0; x1 = n1; ++t; }
;         for (; t + 1 < 31; t += 2) { AT_BODY(0, t, -1.0f, x0, x1, n0, n1); AT_BODY(0, t + 1, -1.0f, n0, n1, x0, x1); }
.LBB0_601:
	s_add_i32 s30, s20, 2
	s_add_i32 s21, s21, 0x8000
	s_addk_i32 s28, 0x80
	s_add_i32 s12, s20, 4
	s_add_u32 s84, s84, s26
	s_addc_u32 s85, s85, s27
	s_add_u32 s86, s86, s24
	s_addc_u32 s87, s87, s25
	s_cmp_lt_u32 s12, s16
	s_cbranch_scc0 .LBB0_606
	s_mov_b32 s20, s30
	s_branch .LBB0_583

; template <bool STORE> __device__ __forceinline__ void attn_unit(LAS unsigned char* lds, bf16_t* Q, const bf16_t* Kg, const bf16_t* VT, const float* subg, float lam, float outscale, int unit, const int wave_s) {
;     ...
;     { const int kr = 8 * wid + (lane >> 4), kc = (lane & 15) ^ (kr & 15); kgp = Kg + (size_t)(b * SEQ + kr) * DM + h * 128 + kc * 8;
;       const int vr = 16 * wid + (lane >> 3), vc = (lane & 7) ^ ((vr >> 1) & 7); vgp = VT + (size_t)(h * 128 + vr) * T + b * SEQ + vc * 8; }
;     const int kx1 = ((((lane & 15) ^ ((8 * wid + (lane >> 4) + 4) & 15)) - ((lane & 15) ^ ((8 * wid + (lane >> 4)) & 15))) * 8) + 4 * DM;
;     const int vx1 = ((((lane & 7) ^ (((16 * wid + (lane >> 3) + 8) >> 1) & 7)) - ((lane & 7) ^ (((16 * wid + (lane >> 3)) >> 1) & 7))) * 8) + 8 * T;
;     const unsigned kdst = lds0 + wid * 2048, vdst = lds0 + AT_VOFF + wid * 2048;
;     ...
;         for (; t + 1 < 31; t += 2) { AT_BODY(0, t, -1.0f, x0, x1, n0, n1); AT_BODY(0, t + 1, -1.0f, n0, n1, x0, x1); }
;         if (t < 31) { AT_BODY(0, t, -1.0f, x0, x1, n0, n1); x0 = n0; x1 = n1; ++t; }
.LBB0_632:
	v_sub_f32_e64 v2, -v166, v166
	s_cmp_gt_i32 s16, 29
	v_sub_f32_e32 v3, v2, v166
	v_add_f32_e32 v13, v2, v2
	s_cbranch_scc1 .LBB0_659
	v_readlane_b32 s21, v253, 23
	s_add_i32 s21, s34, s21
	v_xor_b32_e32 v0, 0x10020, v215
	v_add_u32_e32 v4, s21, v216
	v_add_u32_e32 v167, 0, v0
	v_xor_b32_e32 v0, 0x10040, v215
	s_lshl_b32 s12, s16, 14
	v_ashrrev_i32_e32 v5, 31, v4
	v_add_u32_e32 v168, 0, v0
	v_xor_b32_e32 v0, 0x10060, v215
	s_add_i32 s20, s12, 0x14000
	s_lshl_b64 s[12:13], s[16:17], 17
	v_lshlrev_b64 v[4:5], 11, v[4:5]
	v_add_u32_e32 v180, 0, v0
	v_lshl_add_u64 v[4:5], s[12:13], 0, v[4:5]
	s_and_b32 s12, s18, 0x700
	v_add_u32_e32 v0, s19, v218
	v_or3_b32 v4, v4, s12, v178
	v_lshlrev_b64 v[6:7], 15, v[0:1]
	s_lshl_b64 s[12:13], s[16:17], 7
	v_fma_f32 v14, 2.0, v2, v13
	v_lshl_add_u64 v[6:7], v[6:7], 0, s[12:13]
	v_fma_f32 v15, 2.0, v13, v14
	v_lshl_or_b32 v6, v217, 4, v6
	s_lshl_b32 s12, s16, 6
	v_fmac_f32_e32 v15, 2.0, v14
	v_lshl_add_u64 v[6:7], s[34:35], 1, v[6:7]
	s_add_i32 s18, s12, 0x80
	s_mov_b32 s84, s10
	s_mov_b32 s85, s11
	s_mov_b32 s86, s10
	s_mov_b32 s87, s11
	s_branch .LBB0_635
.LBB0_634:
	s_add_i32 s16, s16, 2
	s_add_i32 s20, s20, 0x8000
	s_add_u32 s84, s84, s26
	s_addc_u32 s85, s85, s27
	s_add_u32 s86, s86, s24
	s_addc_u32 s87, s87, s25
	s_andn2_b64 vcc, exec, s[12:13]
	s_addk_i32 s18, 0x80
	s_cbranch_vccz .LBB0_659
.LBB0_635:
	s_cmp_gt_u32 s16, 27
	s_cselect_b64 s[12:13], -1, 0
	s_mov_b64 s[34:35], -1
	s_and_b64 vcc, exec, s[12:13]
	s_cbranch_vccz .LBB0_639
	s_cmp_eq_u32 s20, 0x88000
	s_cbranch_scc1 .LBB0_638
	s_add_i32 s19, s20, 0xffff8000
	s_and_b32 s19, s19, 0xc000
	s_add_i32 s19, s19, s3
	s_add_u32 s94, s86, s74
	s_addc_u32 s95, s87, s75
	s_mov_b32 m0, s19
	s_nop 0
	global_load_lds_dwordx4 v6, s[94:95]
	v_lshl_add_u32 v8, v172, 1, v6
	s_addk_i32 s19, 0x400
	s_mov_b32 m0, s19
	s_nop 0
	global_load_lds_dwordx4 v8, s[94:95]

.LBB0_639:
	s_andn2_b64 vcc, exec, s[34:35]
	v_lshl_add_u32 v10, v170, 1, v4
	v_lshl_add_u32 v8, v172, 1, v6
	s_cbranch_vccnz .LBB0_641
	s_add_i32 s19, s20, 0xfffec000
	s_and_b32 s19, s19, 0xc000
	s_add_i32 s19, s19, s37
	s_add_u32 s94, s84, s56
	s_addc_u32 s95, s85, s57
	s_mov_b32 m0, s19
	s_nop 0
	global_load_lds_dwordx4 v4, s[94:95]
	s_addk_i32 s19, 0x400
	s_mov_b32 m0, s19
	s_nop 0
	global_load_lds_dwordx4 v10, s[94:95]
	s_add_i32 s19, s20, 0xffff8000
	s_and_b32 s19, s19, 0xc000
	s_add_u32 s94, s86, s74
	s_addc_u32 s95, s87, s75
	s_add_i32 s19, s19, s3
	s_mov_b32 m0, s19
	s_nop 0
	global_load_lds_dwordx4 v6, s[94:95]
	s_addk_i32 s19, 0x400
	s_mov_b32 m0, s19
	s_nop 0
	global_load_lds_dwordx4 v8, s[94:95]

.LBB0_651:
	s_andn2_b64 vcc, exec, s[40:41]
	s_cbranch_vccnz .LBB0_653
	s_and_b32 s28, s20, 0xc000
	s_mov_b64 s[40:41], 0x8da0000
	s_add_u32 s94, s84, 0x8da0000
	s_addc_u32 s95, s85, 0
	s_add_i32 s28, s28, s37
	s_mov_b32 m0, s28
	s_nop 0
	global_load_lds_dwordx4 v4, s[94:95]
	s_addk_i32 s28, 0x400
	s_mov_b32 m0, s28
	s_nop 0
	global_load_lds_dwordx4 v10, s[94:95]
	s_add_u32 s94, s86, s88
	s_addc_u32 s95, s87, s89
	s_add_i32 s21, s21, s3
	s_mov_b32 m0, s21
	s_nop 0
	global_load_lds_dwordx4 v6, s[94:95]
	s_addk_i32 s21, 0x400
	s_mov_b32 m0, s21
	s_nop 0
	global_load_lds_dwordx4 v8, s[94:95]
